# scan consumer: the LDS-DMA'd V rows are awaited (counted vmcnt) right before the fetching wave's own V reads of the next iteration instead of at the workgroup barrier (drains only at iteration 0); dea
# baseline (speedup 1.0000x reference)
.LBB0_320:
	s_cmp_lg_u32 s19, 0
	s_cbranch_scc1 .Lscan_bar_nz
	s_waitcnt vmcnt(0)

.Lscan_vdma_skip:
	s_add_i32 s20, s19, -1
	s_cmp_ge_u32 s20, s17
	s_cbranch_scc1 .LBB0_320
	s_andn2_b32 s22, 1, s19
	s_mul_i32 s20, s22, 0x6c00
	s_add_i32 s20, s20, 0
	v_add_u32_e32 v0, s20, v179
	v_add_u32_e32 v3, s20, v180
	v_add_u32_e32 v1, 0x2000, v0
	v_add_u32_e32 v162, 0x2000, v3
	ds_read2_b64 v[136:139], v1 offset0:32 offset1:36
	s_waitcnt lgkmcnt(1)
	ds_read2_b64 v[144:147], v162 offset0:32 offset1:36
	ds_read2_b64 v[132:135], v0 offset1:4
	ds_read2_b64 v[140:143], v3 offset1:4
	s_mul_i32 s21, s22, 0xffffd400
	s_add_i32 s21, s20, s21
	s_mul_i32 s22, s22, 0x8200
	s_waitcnt lgkmcnt(1)
	v_mfma_f32_16x16x32_bf16 v[132:135], v[136:139], v[132:135], 0
	s_waitcnt lgkmcnt(0)
	v_mfma_f32_16x16x32_bf16 v[136:139], v[136:139], v[140:143], 0
	v_mfma_f32_16x16x32_bf16 v[140:143], v[144:147], v[140:143], 0
	ds_read2_b64 v[144:147], v0 offset0:8 offset1:12
	ds_read2_b64 v[148:151], v1 offset0:40 offset1:44
	ds_read2_b64 v[152:155], v3 offset0:8 offset1:12
	ds_read2_b64 v[156:159], v162 offset0:40 offset1:44
	s_waitcnt lgkmcnt(2)
	v_mfma_f32_16x16x32_bf16 v[132:135], v[148:151], v[144:147], v[132:135]
	s_waitcnt lgkmcnt(1)
	v_mfma_f32_16x16x32_bf16 v[136:139], v[148:151], v[152:155], v[136:139]
	s_waitcnt lgkmcnt(0)
	v_mfma_f32_16x16x32_bf16 v[140:143], v[156:159], v[152:155], v[140:143]
	ds_read2_b64 v[144:147], v0 offset0:16 offset1:20
	ds_read2_b64 v[148:151], v1 offset0:48 offset1:52
	ds_read2_b64 v[152:155], v3 offset0:16 offset1:20
	ds_read2_b64 v[156:159], v162 offset0:48 offset1:52
	s_waitcnt lgkmcnt(2)
	v_mfma_f32_16x16x32_bf16 v[132:135], v[148:151], v[144:147], v[132:135]
	s_waitcnt lgkmcnt(1)
	v_mfma_f32_16x16x32_bf16 v[136:139], v[148:151], v[152:155], v[136:139]
	s_waitcnt lgkmcnt(0)
	v_mfma_f32_16x16x32_bf16 v[140:143], v[156:159], v[152:155], v[140:143]
	ds_read2_b64 v[144:147], v0 offset0:24 offset1:28
	ds_read2_b64 v[148:151], v1 offset0:56 offset1:60
	ds_read2_b64 v[152:155], v3 offset0:24 offset1:28
	ds_read2_b64 v[156:159], v162 offset0:56 offset1:60
	s_waitcnt lgkmcnt(2)
	v_mfma_f32_16x16x32_bf16 v[132:135], v[148:151], v[144:147], v[132:135]
	s_waitcnt lgkmcnt(0)
	v_mfma_f32_16x16x32_bf16 v[140:143], v[156:159], v[152:155], v[140:143]
	s_nop 5
	v_cndmask_b32_e64 v0, v132, 0, s[38:39]
	v_cndmask_b32_e64 v1, 0, v133, s[40:41]
	v_cndmask_b32_e64 v3, v134, 0, s[42:43]
	v_cndmask_b32_e64 v144, v135, 0, s[44:45]
	v_mfma_f32_16x16x32_bf16 v[132:135], v[148:151], v[152:155], v[136:139]
	v_cndmask_b32_e64 v140, v140, 0, s[38:39]
	v_cndmask_b32_e64 v141, 0, v141, s[40:41]
	v_cndmask_b32_e64 v142, v142, 0, s[42:43]
	v_cndmask_b32_e64 v143, v143, 0, s[44:45]
	v_cvt_pk_bf16_f32 v0, v0, v1
	v_cvt_pk_bf16_f32 v1, v3, v144
	v_mov_b32_e32 v3, v2
	s_nop 0
	v_cvt_pk_bf16_f32 v132, v132, v133
	v_cvt_pk_bf16_f32 v133, v134, v135
	v_cvt_pk_bf16_f32 v134, v140, v141
	v_cvt_pk_bf16_f32 v135, v142, v143
	v_add_u32_e32 v136, s21, v181
	v_add_u32_e32 v191, v136, v173
	v_add_u32_e32 v192, v136, v175
	s_cmp_ge_u32 s19, s17
	s_cbranch_scc1 .Lscan_vw0
	s_waitcnt vmcnt(4)
	s_branch .Lscan_vw1

.Lscan_vw1:
	ds_read2st64_b64 v[142:145], v191 offset0:108 offset1:110
	ds_read2st64_b64 v[136:139], v192 offset0:108 offset1:110
	v_add_u32_e32 v162, s20, v172
	v_add_u32_e32 v186, v162, v178
	v_add_u32_e32 v171, 0x1000, v186
	s_waitcnt lgkmcnt(1)
	v_mov_b32_e32 v140, v142
	v_mov_b32_e32 v141, v143
	s_waitcnt lgkmcnt(0)
	v_mov_b32_e32 v142, v136
	v_mov_b32_e32 v143, v137
	v_mov_b32_e32 v136, v144
	v_mov_b32_e32 v137, v145
	ds_read2_b64 v[144:147], v186 offset1:4
	ds_read2_b64 v[148:151], v171 offset0:16 offset1:20
	v_cvt_pk_bf16_f32 v152, v4, v5
	v_cvt_pk_bf16_f32 v153, v6, v7
	v_cvt_pk_bf16_f32 v154, v20, v21
	v_cvt_pk_bf16_f32 v155, v22, v23
	v_cvt_pk_bf16_f32 v194, v8, v9
	v_cvt_pk_bf16_f32 v195, v10, v11
	v_cvt_pk_bf16_f32 v196, v24, v25
	v_cvt_pk_bf16_f32 v197, v26, v27
	s_waitcnt lgkmcnt(1)
	v_mfma_f32_16x16x32_bf16 v[156:159], v[144:147], v[152:155], 0
	v_cvt_pk_bf16_f32 v216, v36, v37
	v_cvt_pk_bf16_f32 v217, v38, v39
	v_cvt_pk_bf16_f32 v218, v52, v53
	s_waitcnt lgkmcnt(0)
	v_mfma_f32_16x16x32_bf16 v[152:155], v[148:151], v[152:155], 0
	v_cvt_pk_bf16_f32 v219, v54, v55
	v_add_u32_e32 v163, v162, v182
	v_add_u32_e32 v169, s20, v176
	v_mfma_f32_16x16x32_bf16 v[144:147], v[144:147], v[194:197], 0
	v_add_u32_e32 v162, v162, v183
	v_add_u32_e32 v188, 0x5000, v163
	v_add_u32_e32 v193, 0x5800, v163
	v_mfma_f32_16x16x32_bf16 v[148:151], v[148:151], v[194:197], 0
	ds_read2_b64 v[194:197], v186 offset0:8 offset1:12
	ds_read2_b64 v[198:201], v171 offset0:24 offset1:28
	v_add_u32_e32 v187, 0x6000, v163
	v_add_u32_e32 v190, s22, v177
	s_waitcnt lgkmcnt(1)
	v_mfma_f32_16x16x32_bf16 v[156:159], v[194:197], v[216:219], v[156:159]
	v_add_u32_e32 v189, v190, v184
	v_add_u32_e32 v190, v190, v185
	s_waitcnt lgkmcnt(0)
	v_mfma_f32_16x16x32_bf16 v[152:155], v[198:201], v[216:219], v[152:155]
	v_cvt_pk_bf16_f32 v216, v40, v41
	v_cvt_pk_bf16_f32 v217, v42, v43
	v_cvt_pk_bf16_f32 v218, v56, v57
	v_cvt_pk_bf16_f32 v219, v58, v59
	s_nop 1
	v_mfma_f32_16x16x32_bf16 v[144:147], v[194:197], v[216:219], v[144:147]
	v_mfma_f32_16x16x32_bf16 v[148:151], v[198:201], v[216:219], v[148:151]
	ds_read2_b64 v[194:197], v186 offset0:16 offset1:20
	ds_read2_b64 v[198:201], v171 offset0:32 offset1:36
	v_cvt_pk_bf16_f32 v216, v68, v69
	v_cvt_pk_bf16_f32 v217, v70, v71
	v_cvt_pk_bf16_f32 v218, v84, v85
	v_cvt_pk_bf16_f32 v219, v86, v87
	s_waitcnt lgkmcnt(1)
	s_nop 0
	v_mfma_f32_16x16x32_bf16 v[156:159], v[194:197], v[216:219], v[156:159]
	s_waitcnt lgkmcnt(0)
	v_mfma_f32_16x16x32_bf16 v[152:155], v[198:201], v[216:219], v[152:155]
	v_cvt_pk_bf16_f32 v216, v72, v73
	v_cvt_pk_bf16_f32 v217, v74, v75
	v_cvt_pk_bf16_f32 v218, v88, v89
	v_cvt_pk_bf16_f32 v219, v90, v91
	s_nop 1
	v_mfma_f32_16x16x32_bf16 v[144:147], v[194:197], v[216:219], v[144:147]
	v_mfma_f32_16x16x32_bf16 v[148:151], v[198:201], v[216:219], v[148:151]
	ds_read2_b64 v[194:197], v186 offset0:24 offset1:28
	ds_read2_b64 v[198:201], v171 offset0:40 offset1:44
	v_cvt_pk_bf16_f32 v216, v100, v101
	v_cvt_pk_bf16_f32 v217, v102, v103
	v_cvt_pk_bf16_f32 v218, v124, v125
	v_cvt_pk_bf16_f32 v219, v126, v127
	s_waitcnt lgkmcnt(1)
	s_nop 0
	v_mfma_f32_16x16x32_bf16 v[156:159], v[194:197], v[216:219], v[156:159]
	s_waitcnt lgkmcnt(0)
	v_mfma_f32_16x16x32_bf16 v[216:219], v[198:201], v[216:219], v[152:155]
	s_nop 2
	v_cvt_pk_bf16_f32 v152, v104, v105
	v_cvt_pk_bf16_f32 v153, v106, v107
	v_cvt_pk_bf16_f32 v154, v116, v117
	v_cvt_pk_bf16_f32 v155, v118, v119
	s_nop 1
	v_mfma_f32_16x16x32_bf16 v[194:197], v[194:197], v[152:155], v[144:147]
	v_mfma_f32_16x16x32_bf16 v[148:151], v[198:201], v[152:155], v[148:151]
	v_mfma_f32_16x16x32_bf16 v[152:155], v[0:3], v[140:143], v[156:159]
	v_mfma_f32_16x16x32_bf16 v[156:159], v[0:3], v[136:139], v[194:197]
	s_nop 4
	v_add_u32_e32 v196, 0x4000, v163
	v_mfma_f32_16x16x32_bf16 v[144:147], v[132:135], v[140:143], v[216:219]
	ds_read2_b64 v[198:201], v196 offset0:64 offset1:68
	s_nop 1
	ds_read_b128 v[216:219], v169 offset:27136
	v_add_u32_e32 v194, 0x4000, v162
	v_add_u32_e32 v195, 0x4800, v163
	s_waitcnt lgkmcnt(1)
	v_mfma_f32_16x16x32_bf16 v[4:7], v[198:201], v[140:143], v[4:7]
	v_mfma_f32_16x16x32_bf16 v[8:11], v[198:201], v[136:139], v[8:11]
	s_waitcnt lgkmcnt(0)
	s_nop 5
	v_pk_mul_f32 v[6:7], v[218:219], v[6:7]
	v_pk_mul_f32 v[4:5], v[216:217], v[4:5]
	v_mfma_f32_16x16x32_bf16 v[148:151], v[132:135], v[136:139], v[148:151]
	v_mul_f32_e64 v10, v218, v10
	v_mul_f32_e64 v11, v219, v11
	v_pk_mul_f32 v[8:9], v[216:217], v[8:9]
	ds_read2_b64 v[198:201], v194 offset0:64 offset1:68
	ds_read_b128 v[216:219], v169 offset:27200
	s_waitcnt lgkmcnt(1)
	v_mfma_f32_16x16x32_bf16 v[20:23], v[198:201], v[140:143], v[20:23]
	v_mfma_f32_16x16x32_bf16 v[24:27], v[198:201], v[136:139], v[24:27]
	s_waitcnt lgkmcnt(0)
	s_nop 5
	v_pk_mul_f32 v[22:23], v[218:219], v[22:23]
	v_pk_mul_f32 v[20:21], v[216:217], v[20:21]
	v_pk_mul_f32 v[26:27], v[218:219], v[26:27]
	v_pk_mul_f32 v[24:25], v[216:217], v[24:25]
	ds_read2_b64 v[198:201], v195 offset0:128 offset1:132
	ds_read_b128 v[216:219], v169 offset:27264
	s_waitcnt lgkmcnt(1)
	v_mfma_f32_16x16x32_bf16 v[36:39], v[198:201], v[140:143], v[36:39]
	v_mfma_f32_16x16x32_bf16 v[40:43], v[198:201], v[136:139], v[40:43]
	s_waitcnt lgkmcnt(0)
	s_nop 5
	v_pk_mul_f32 v[38:39], v[218:219], v[38:39]
	v_pk_mul_f32 v[36:37], v[216:217], v[36:37]
	v_pk_mul_f32 v[42:43], v[218:219], v[42:43]
	v_pk_mul_f32 v[40:41], v[216:217], v[40:41]
	ds_read2_b64 v[198:201], v188 offset0:32 offset1:36
	ds_read_b128 v[216:219], v169 offset:27328
	s_waitcnt lgkmcnt(1)
	v_mfma_f32_16x16x32_bf16 v[52:55], v[198:201], v[140:143], v[52:55]
	v_mfma_f32_16x16x32_bf16 v[56:59], v[198:201], v[136:139], v[56:59]
	s_waitcnt lgkmcnt(0)
	s_nop 5
	v_pk_mul_f32 v[54:55], v[218:219], v[54:55]
	v_pk_mul_f32 v[52:53], v[216:217], v[52:53]
	v_pk_mul_f32 v[58:59], v[218:219], v[58:59]
	v_pk_mul_f32 v[56:57], v[216:217], v[56:57]
	ds_read2_b64 v[198:201], v188 offset0:192 offset1:196
	ds_read_b128 v[216:219], v169 offset:27392
	s_waitcnt lgkmcnt(1)
	v_mfma_f32_16x16x32_bf16 v[68:71], v[198:201], v[140:143], v[68:71]
	v_mfma_f32_16x16x32_bf16 v[72:75], v[198:201], v[136:139], v[72:75]
	s_waitcnt lgkmcnt(0)
	s_nop 5
	v_pk_mul_f32 v[70:71], v[218:219], v[70:71]
	v_pk_mul_f32 v[68:69], v[216:217], v[68:69]
	v_pk_mul_f32 v[74:75], v[218:219], v[74:75]
	v_pk_mul_f32 v[72:73], v[216:217], v[72:73]
	ds_read2_b64 v[198:201], v193 offset0:96 offset1:100
	ds_read_b128 v[216:219], v169 offset:27456
	s_waitcnt lgkmcnt(1)
	v_mfma_f32_16x16x32_bf16 v[84:87], v[198:201], v[140:143], v[84:87]
	v_mfma_f32_16x16x32_bf16 v[88:91], v[198:201], v[136:139], v[88:91]
	s_waitcnt lgkmcnt(0)
	s_nop 5
	v_pk_mul_f32 v[86:87], v[218:219], v[86:87]
	v_pk_mul_f32 v[84:85], v[216:217], v[84:85]
	v_pk_mul_f32 v[90:91], v[218:219], v[90:91]
	v_pk_mul_f32 v[88:89], v[216:217], v[88:89]
	ds_read2_b64 v[198:201], v187 offset1:4
	ds_read_b128 v[216:219], v169 offset:27520
	s_waitcnt lgkmcnt(1)
	v_mfma_f32_16x16x32_bf16 v[100:103], v[198:201], v[140:143], v[100:103]
	v_mfma_f32_16x16x32_bf16 v[104:107], v[198:201], v[136:139], v[104:107]
	s_waitcnt lgkmcnt(0)
	s_nop 5
	v_pk_mul_f32 v[102:103], v[218:219], v[102:103]
	v_pk_mul_f32 v[100:101], v[216:217], v[100:101]
	v_pk_mul_f32 v[106:107], v[218:219], v[106:107]
	v_pk_mul_f32 v[104:105], v[216:217], v[104:105]
	ds_read2_b64 v[198:201], v187 offset0:160 offset1:164
	ds_read_b128 v[216:219], v169 offset:27584
	s_waitcnt lgkmcnt(1)
	v_mfma_f32_16x16x32_bf16 v[124:127], v[198:201], v[140:143], v[124:127]
	ds_write_b32 v189, v152
	ds_write_b32 v189, v153 offset:1040
	ds_write_b32 v190, v154
	ds_write_b32 v190, v155 offset:1040
	ds_write_b32 v189, v156 offset:64
	ds_write_b32 v189, v157 offset:1104
	ds_write_b32 v190, v158 offset:64
	ds_write_b32 v190, v159 offset:1104
	v_add_u32_e32 v156, 0x4000, v189
	v_mfma_f32_16x16x32_bf16 v[116:119], v[198:201], v[136:139], v[116:119]
	s_waitcnt lgkmcnt(8)
	v_pk_mul_f32 v[126:127], v[218:219], v[126:127]
	v_pk_mul_f32 v[124:125], v[216:217], v[124:125]
	v_add_u32_e32 v157, 0x4400, v189
	v_add_u32_e32 v158, 0x4800, v189
	v_add_u32_e32 v159, 0x4c00, v189
	s_nop 1
	v_pk_mul_f32 v[118:119], v[218:219], v[118:119]
	v_pk_mul_f32 v[116:117], v[216:217], v[116:117]
	ds_write2_b32 v156, v144, v148 offset0:64 offset1:80
	ds_write2_b32 v157, v145, v149 offset0:68 offset1:84
	ds_write2_b32 v158, v146, v150 offset0:72 offset1:88
	ds_write2_b32 v159, v147, v151 offset0:76 offset1:92
	ds_read2st64_b64 v[142:145], v191 offset0:112 offset1:114
	ds_read2st64_b64 v[136:139], v192 offset0:112 offset1:114
	v_cvt_pk_bf16_f32 v152, v12, v13
	v_cvt_pk_bf16_f32 v153, v14, v15
	v_cvt_pk_bf16_f32 v154, v28, v29
	s_waitcnt lgkmcnt(1)
	v_mov_b32_e32 v140, v142
	v_mov_b32_e32 v141, v143
	s_waitcnt lgkmcnt(0)
	v_mov_b32_e32 v142, v136
	v_mov_b32_e32 v143, v137
	v_mov_b32_e32 v136, v144
	v_mov_b32_e32 v137, v145
	ds_read2_b64 v[144:147], v186 offset1:4
	ds_read2_b64 v[148:151], v171 offset0:16 offset1:20
	v_cvt_pk_bf16_f32 v155, v30, v31
	v_cvt_pk_bf16_f32 v216, v16, v17
	v_cvt_pk_bf16_f32 v217, v18, v19
	v_cvt_pk_bf16_f32 v218, v32, v33
	v_cvt_pk_bf16_f32 v219, v34, v35
	s_waitcnt lgkmcnt(1)
	v_mfma_f32_16x16x32_bf16 v[198:201], v[144:147], v[152:155], 0
	v_cvt_pk_bf16_f32 v224, v44, v45
	v_cvt_pk_bf16_f32 v225, v46, v47
	v_cvt_pk_bf16_f32 v226, v60, v61
	s_waitcnt lgkmcnt(0)
	v_mfma_f32_16x16x32_bf16 v[152:155], v[148:151], v[152:155], 0
	v_cvt_pk_bf16_f32 v227, v62, v63
	v_mfma_f32_16x16x32_bf16 v[144:147], v[144:147], v[216:219], 0
	v_mfma_f32_16x16x32_bf16 v[148:151], v[148:151], v[216:219], 0
	ds_read2_b64 v[216:219], v186 offset0:8 offset1:12
	ds_read2_b64 v[220:223], v171 offset0:24 offset1:28
	s_waitcnt lgkmcnt(1)
	v_mfma_f32_16x16x32_bf16 v[198:201], v[216:219], v[224:227], v[198:201]
	s_waitcnt lgkmcnt(0)
	v_mfma_f32_16x16x32_bf16 v[152:155], v[220:223], v[224:227], v[152:155]
	v_cvt_pk_bf16_f32 v224, v48, v49
	v_cvt_pk_bf16_f32 v225, v50, v51
	v_cvt_pk_bf16_f32 v226, v64, v65
	v_cvt_pk_bf16_f32 v227, v66, v67
	s_nop 1
	v_mfma_f32_16x16x32_bf16 v[144:147], v[216:219], v[224:227], v[144:147]
	v_mfma_f32_16x16x32_bf16 v[148:151], v[220:223], v[224:227], v[148:151]
	ds_read2_b64 v[216:219], v186 offset0:16 offset1:20
	ds_read2_b64 v[220:223], v171 offset0:32 offset1:36
	v_cvt_pk_bf16_f32 v224, v76, v77
	v_cvt_pk_bf16_f32 v225, v78, v79
	v_cvt_pk_bf16_f32 v226, v92, v93
	v_cvt_pk_bf16_f32 v227, v94, v95
	s_waitcnt lgkmcnt(1)
	s_nop 0
	v_mfma_f32_16x16x32_bf16 v[198:201], v[216:219], v[224:227], v[198:201]
	s_waitcnt lgkmcnt(0)
	v_mfma_f32_16x16x32_bf16 v[152:155], v[220:223], v[224:227], v[152:155]
	v_cvt_pk_bf16_f32 v224, v80, v81
	v_cvt_pk_bf16_f32 v225, v82, v83
	v_cvt_pk_bf16_f32 v226, v96, v97
	v_cvt_pk_bf16_f32 v227, v98, v99
	s_nop 1
	v_mfma_f32_16x16x32_bf16 v[144:147], v[216:219], v[224:227], v[144:147]
	v_mfma_f32_16x16x32_bf16 v[148:151], v[220:223], v[224:227], v[148:151]
	ds_read2_b64 v[216:219], v186 offset0:24 offset1:28
	ds_read2_b64 v[220:223], v171 offset0:40 offset1:44
	v_cvt_pk_bf16_f32 v224, v108, v109
	v_cvt_pk_bf16_f32 v225, v110, v111
	v_cvt_pk_bf16_f32 v226, v120, v121
	v_cvt_pk_bf16_f32 v227, v122, v123
	s_waitcnt lgkmcnt(1)
	s_nop 0
	v_mfma_f32_16x16x32_bf16 v[198:201], v[216:219], v[224:227], v[198:201]
	s_waitcnt lgkmcnt(0)
	v_mfma_f32_16x16x32_bf16 v[224:227], v[220:223], v[224:227], v[152:155]
	s_nop 2
	v_cvt_pk_bf16_f32 v152, v112, v113
	v_cvt_pk_bf16_f32 v153, v114, v115
	v_cvt_pk_bf16_f32 v154, v128, v129
	v_cvt_pk_bf16_f32 v155, v130, v131
	s_nop 1
	v_mfma_f32_16x16x32_bf16 v[216:219], v[216:219], v[152:155], v[144:147]
	v_mfma_f32_16x16x32_bf16 v[220:223], v[220:223], v[152:155], v[148:151]
	v_mfma_f32_16x16x32_bf16 v[152:155], v[0:3], v[140:143], v[198:201]
	s_nop 2
	ds_read2_b64 v[196:199], v196 offset0:64 offset1:68
	ds_read_b128 v[200:203], v169 offset:27136
	s_waitcnt lgkmcnt(1)
	v_mfma_f32_16x16x32_bf16 v[12:15], v[196:199], v[140:143], v[12:15]
	v_mfma_f32_16x16x32_bf16 v[16:19], v[196:199], v[136:139], v[16:19]
	s_waitcnt lgkmcnt(0)
	s_nop 5
	v_pk_mul_f32 v[14:15], v[202:203], v[14:15]
	v_pk_mul_f32 v[12:13], v[200:201], v[12:13]
	v_mfma_f32_16x16x32_bf16 v[144:147], v[132:135], v[140:143], v[224:227]
	v_mfma_f32_16x16x32_bf16 v[148:151], v[0:3], v[136:139], v[216:219]
	v_mul_f32_e64 v18, v202, v18
	v_mul_f32_e64 v19, v203, v19
	v_pk_mul_f32 v[16:17], v[200:201], v[16:17]
	ds_read2_b64 v[196:199], v194 offset0:64 offset1:68
	ds_read_b128 v[200:203], v169 offset:27200
	s_waitcnt lgkmcnt(1)
	v_mfma_f32_16x16x32_bf16 v[28:31], v[196:199], v[140:143], v[28:31]
	v_mfma_f32_16x16x32_bf16 v[32:35], v[196:199], v[136:139], v[32:35]
	s_waitcnt lgkmcnt(0)
	s_nop 5
	v_pk_mul_f32 v[28:29], v[200:201], v[28:29]
	v_pk_mul_f32 v[30:31], v[202:203], v[30:31]
	v_mfma_f32_16x16x32_bf16 v[132:135], v[132:135], v[136:139], v[220:223]
	v_mul_f32_e64 v32, v200, v32
	v_mul_f32_e64 v33, v201, v33
	ds_read2_b64 v[194:197], v195 offset0:128 offset1:132
	ds_read_b128 v[198:201], v169 offset:27264
	s_waitcnt lgkmcnt(1)
	v_mfma_f32_16x16x32_bf16 v[44:47], v[194:197], v[140:143], v[44:47]
	v_mul_f32_e64 v34, v202, v34
	v_mul_f32_e64 v35, v203, v35
	v_mfma_f32_16x16x32_bf16 v[48:51], v[194:197], v[136:139], v[48:51]
	s_waitcnt lgkmcnt(0)
	s_nop 3
	v_pk_mul_f32 v[46:47], v[200:201], v[46:47]
	v_pk_mul_f32 v[44:45], v[198:199], v[44:45]
	s_nop 0
	v_pk_mul_f32 v[50:51], v[200:201], v[50:51]
	v_pk_mul_f32 v[48:49], v[198:199], v[48:49]
	ds_read2_b64 v[194:197], v188 offset0:32 offset1:36
	ds_read_b128 v[198:201], v169 offset:27328
	s_waitcnt lgkmcnt(1)
	v_mfma_f32_16x16x32_bf16 v[60:63], v[194:197], v[140:143], v[60:63]
	v_mfma_f32_16x16x32_bf16 v[64:67], v[194:197], v[136:139], v[64:67]
	s_waitcnt lgkmcnt(0)
	s_nop 5
	v_pk_mul_f32 v[62:63], v[200:201], v[62:63]
	v_pk_mul_f32 v[60:61], v[198:199], v[60:61]
	v_pk_mul_f32 v[66:67], v[200:201], v[66:67]
	v_pk_mul_f32 v[64:65], v[198:199], v[64:65]
	ds_read2_b64 v[194:197], v188 offset0:192 offset1:196
	ds_read_b128 v[198:201], v169 offset:27392
	s_waitcnt lgkmcnt(1)
	v_mfma_f32_16x16x32_bf16 v[76:79], v[194:197], v[140:143], v[76:79]
	v_mfma_f32_16x16x32_bf16 v[80:83], v[194:197], v[136:139], v[80:83]
	s_waitcnt lgkmcnt(0)
	s_nop 5
	v_pk_mul_f32 v[76:77], v[198:199], v[76:77]
	v_pk_mul_f32 v[78:79], v[200:201], v[78:79]
	v_pk_mul_f32 v[80:81], v[198:199], v[80:81]
	ds_read2_b64 v[192:195], v193 offset0:96 offset1:100
	ds_read_b128 v[196:199], v169 offset:27456
	s_waitcnt lgkmcnt(1)
	v_mfma_f32_16x16x32_bf16 v[92:95], v[192:195], v[140:143], v[92:95]
	v_mul_f32_e64 v82, v200, v82
	v_mul_f32_e64 v83, v201, v83
	v_mfma_f32_16x16x32_bf16 v[96:99], v[192:195], v[136:139], v[96:99]
	s_waitcnt lgkmcnt(0)
	s_nop 3
	v_pk_mul_f32 v[94:95], v[198:199], v[94:95]
	v_pk_mul_f32 v[92:93], v[196:197], v[92:93]
	s_nop 0
	v_pk_mul_f32 v[98:99], v[198:199], v[98:99]
	v_pk_mul_f32 v[96:97], v[196:197], v[96:97]
	ds_read2_b64 v[192:195], v187 offset1:4
	ds_read_b128 v[196:199], v169 offset:27520
	s_waitcnt lgkmcnt(1)
	v_mfma_f32_16x16x32_bf16 v[108:111], v[192:195], v[140:143], v[108:111]
	v_mfma_f32_16x16x32_bf16 v[112:115], v[192:195], v[136:139], v[112:115]
	s_waitcnt lgkmcnt(0)
	s_nop 5
	v_pk_mul_f32 v[110:111], v[198:199], v[110:111]
	v_pk_mul_f32 v[108:109], v[196:197], v[108:109]
	v_pk_mul_f32 v[114:115], v[198:199], v[114:115]
	v_pk_mul_f32 v[112:113], v[196:197], v[112:113]
	ds_read2_b64 v[192:195], v187 offset0:160 offset1:164
	ds_read_b128 v[196:199], v169 offset:27584
	s_waitcnt lgkmcnt(1)
	v_mfma_f32_16x16x32_bf16 v[120:123], v[192:195], v[140:143], v[120:123]
	ds_write_b32 v189, v152 offset:128
	ds_write_b32 v189, v153 offset:1168
	ds_write_b32 v190, v154 offset:128
	ds_write_b32 v190, v155 offset:1168
	ds_write_b32 v189, v148 offset:192
	ds_write_b32 v189, v149 offset:1232
	ds_write_b32 v190, v150 offset:192
	ds_write_b32 v190, v151 offset:1232
	ds_write2_b32 v156, v144, v132 offset0:96 offset1:112
	ds_write2_b32 v157, v145, v133 offset0:100 offset1:116
	ds_write2_b32 v158, v146, v134 offset0:104 offset1:120
	ds_write2_b32 v159, v147, v135 offset0:108 offset1:124
	s_waitcnt lgkmcnt(12)
	v_pk_mul_f32 v[122:123], v[198:199], v[122:123]
	v_mfma_f32_16x16x32_bf16 v[128:131], v[192:195], v[136:139], v[128:131]
	v_mul_f32_e64 v120, v196, v120
	v_mul_f32_e64 v121, v197, v121
	s_nop 5
	v_pk_mul_f32 v[130:131], v[198:199], v[130:131]
	v_pk_mul_f32 v[128:129], v[196:197], v[128:129]
	s_branch .LBB0_320
